# plus P3 sub-phase order swapped for half the workgroups (branch-projection GEMMs before the LDS FFT stage 2)
# baseline (speedup 1.0000x reference)
; __global__ void __launch_bounds__(512, 2) fwd_megakernel(Params p_) {
;     ...
;             for (int t = bid; t < 1024; t += G) {
;                 int base, k2, cc, lR, lCW;
;                 if (t < 512) { base = (t >> 6) * 2048; const int rem = t & 63; k2 = rem >> 1; cc = rem & 1; lR = 6; lCW = 8; }
;                 else { const int tt = t - 512; base = M_PROMPT + (tt >> 8) * 8192; const int rem = tt & 255; k2 = rem >> 3; cc = rem & 7; lR = 8; lCW = 6; }
;                 const int R = 1 << lR, CWm = (1 << lCW) - 1;
;                 __syncthreads();
;                 if (tid < (R >> 1)) TW[tid] = TWT[(lR == 6 ? TW_RA : TW_RB) + tid];
;                 const f32x2* zsrc = ZB + (size_t)(base + k2 * R) * 512 + (cc << lCW);
; #pragma unroll
;                 for (int ih = 0; ih < 32; ih += 16) { f32x2 zv[16];
; #pragma unroll
;                     for (int it = 0; it < 16; ++it) { const int f = (ih + it) * 512 + tid, c = f & CWm, n1 = f >> lCW; zv[it] = zsrc[(size_t)n1 * 512 + c]; }
; #pragma unroll
;                     for (int it = 0; it < 16; ++it) FX[(ih + it) * 512 + tid] = zv[it]; }
.LBB0_558:
	s_or_b64 exec, exec, s[6:7]
	v_readlane_b32 s2, v253, 0
	v_mov_b32_e32 v6, v246
	v_readlane_b32 s3, v253, 1
	s_waitcnt lgkmcnt(0)
	s_barrier
	v_readlane_b32 s101, v253, 7
	s_nop 0
	s_bfe_u32 s101, s101, 0x10003
	s_load_dwordx2 s[12:13], s[2:3], 0xd0
	v_readlane_b32 s0, v255, 13
	v_readlane_b32 s1, v255, 14
	s_and_b64 vcc, exec, s[0:1]
	s_cbranch_vccnz .LBB0_574
	s_cmp_eq_u32 s101, 1
	s_cbranch_scc1 .LBB0_574
.Lp3_fft2:
	s_waitcnt lgkmcnt(0)
	s_add_u32 s2, s12, 0x40d2a000
	s_addc_u32 s14, s13, 0
	s_add_u32 s15, s12, 0x48d2a000
	s_addc_u32 s16, s13, 0
	v_lshlrev_b32_e32 v0, 3, v6
	s_add_u32 s6, s12, 0x4dd7e000
	v_add_u32_e32 v8, 0, v0
	v_readlane_b32 s4, v253, 7
	s_addc_u32 s7, s13, 0
	v_add_u32_e32 v7, s97, v0
	v_add_u32_e32 v9, 0x200, v6
	v_add_u32_e32 v10, 0x400, v6
	v_add_u32_e32 v11, 0x600, v6
	v_add_u32_e32 v12, 0x800, v6
	v_add_u32_e32 v13, 0xa00, v6
	v_add_u32_e32 v14, 0xc00, v6
	v_add_u32_e32 v15, 0xe00, v6
	v_add_u32_e32 v16, 0x1000, v6
	v_add_u32_e32 v17, 0x1200, v6
	v_add_u32_e32 v18, 0x1400, v6
	v_add_u32_e32 v19, 0x1600, v6
	v_add_u32_e32 v20, 0x1800, v6
	v_add_u32_e32 v21, 0x1a00, v6
	v_add_u32_e32 v22, 0x1c00, v6
	v_add_u32_e32 v23, 0x1e00, v6
	v_add_u32_e32 v24, 0x2000, v6
	v_add_u32_e32 v25, 0x2200, v6
	v_add_u32_e32 v26, 0x2400, v6
	v_add_u32_e32 v27, 0x2600, v6
	v_add_u32_e32 v28, 0x2800, v6
	v_add_u32_e32 v29, 0x2a00, v6
	v_add_u32_e32 v30, 0x2c00, v6
	v_add_u32_e32 v31, 0x2e00, v6
	v_add_u32_e32 v32, 0x3000, v6
	v_add_u32_e32 v33, 0x3200, v6
	v_add_u32_e32 v34, 0x3400, v6
	v_add_u32_e32 v35, 0x3600, v6
	v_add_u32_e32 v36, 0x3800, v6
	v_add_u32_e32 v37, 0x3a00, v6
	v_add_u32_e32 v38, 0x3c00, v6
	v_add_u32_e32 v39, 0x3e00, v6
	v_add_u32_e32 v40, 0x10000, v8
	v_add_u32_e32 v41, 0x11000, v8
	v_add_u32_e32 v42, 0x12000, v8
	v_add_u32_e32 v43, 0x13000, v8
	v_add_u32_e32 v44, 0x14000, v8
	v_add_u32_e32 v45, 0x15000, v8
	v_add_u32_e32 v46, 0x16000, v8
	v_add_u32_e32 v47, 0x17000, v8
	v_add_u32_e32 v48, 0x18000, v8
	v_add_u32_e32 v49, 0x19000, v8
	v_add_u32_e32 v50, 0x1a000, v8
	v_add_u32_e32 v51, 0x1b000, v8
	v_add_u32_e32 v52, 0x1c000, v8
	v_add_u32_e32 v53, 0x1d000, v8
	v_add_u32_e32 v54, 0x1e000, v8
	v_add_u32_e32 v55, 0x1f000, v8
	s_mov_b32 s17, s4
	v_readlane_b32 s5, v253, 8

; __device__ __forceinline__ int opaque_tid() { int t = threadIdx.x; asm volatile("" : "+v"(t)); return t; }
;     __device__ __forceinline__ void init(AccMut acc, const Unit& u, int wr, int wc, int fr, int fq) const { acc_bias(acc, bias + u.pn * 256 + wc * 32 + 8 * fq); }
;     __device__ __forceinline__ void init(AccMut acc, const Unit&, int, int, int, int) const { acc_zero(acc); }
;     __device__ __forceinline__ void init(AccMut acc, const Unit&, int, int, int, int) const { acc_zero(acc); }
;     __device__ __forceinline__ void init(AccMut acc, const Unit& u, int wr, int wc, int fr, int fq) const { acc_bias(acc, bias + u.pn * 256 + wc * 32 + 8 * fq); }
;     __device__ __forceinline__ void init(AccMut acc, const Unit&, int, int, int, int) const { acc_zero(acc); }
;     __device__ __forceinline__ void init(AccMut acc, const Unit&, int, int, int, int) const { acc_zero(acc); }
; __global__ void __launch_bounds__(512, 2) fwd_megakernel(Params p_) {
;     ...
;             __syncthreads();
;             { const int tid = opaque_tid(); pg8::Gemm g{H + SEG_P + 1024, wt + WT_P, M_TOK, DM, 1024, LDP, 1024}; pg8::StaticOrder S; S.init(M_TOK, DM, G, bid);
;               EpiMerge<true> E{MRG, H + SEG_G + (size_t)M_TOK * LDG}; pg8::gemm_phase(lds, g, S, E, tid); }
.LBB0_574:
	s_cmp_eq_u32 s101, 3
	s_cbranch_scc0 .Lp3_c574
	v_readlane_b32 s0, v255, 8
	v_readlane_b32 s1, v255, 9
	s_nop 0
	s_lshl_b64 s[6:7], s[0:1], 1
	s_branch .LBB0_606

; __device__ __forceinline__ int opaque_tid() { int t = threadIdx.x; asm volatile("" : "+v"(t)); return t; }
; #define GRID_SYNC() do { asm volatile("" ::: "memory"); xcd_barrier(xbar); asm volatile("" ::: "memory"); } while (0)
;     __device__ __forceinline__ void init(AccMut acc, const Unit& u, int wr, int wc, int fr, int fq) const { acc_bias(acc, bias + u.pn * 256 + wc * 32 + 8 * fq); }
;     __device__ __forceinline__ void init(AccMut acc, const Unit&, int, int, int, int) const { acc_zero(acc); }
;     __device__ __forceinline__ void init(AccMut acc, const Unit&, int, int, int, int) const { acc_zero(acc); }
;     __device__ __forceinline__ void init(AccMut acc, const Unit& u, int wr, int wc, int fr, int fq) const { acc_bias(acc, bias + u.pn * 256 + wc * 32 + 8 * fq); }
;     __device__ __forceinline__ void init(AccMut acc, const Unit&, int, int, int, int) const { acc_zero(acc); }
;     __device__ __forceinline__ void init(AccMut acc, const Unit&, int, int, int, int) const { acc_zero(acc); }
; __global__ void __launch_bounds__(512, 2) fwd_megakernel(Params p_) {
;     ...
;               EpiMerge<true> E{MRG, H + SEG_G + (size_t)M_TOK * LDG}; pg8::gemm_phase(lds, g, S, E, tid); }
;             { const int tid = opaque_tid(); pg8::Gemm g{H + SEG_C + 512, wt + WT_C, M_TOK, DM, 512, LDC, 512}; pg8::StaticOrder S; S.init(M_TOK, DM, G, bid);
;               EpiMerge<false> E{MRG, H + SEG_G + (size_t)2 * M_TOK * LDG}; pg8::gemm_phase(lds, g, S, E, tid); }
;         }
;         GRID_SYNC();
.LBB0_606:
	s_cmp_eq_u32 s101, 1
	s_cbranch_scc0 .Lp3_cont
	s_mov_b32 s101, 3
	v_mov_b32_e32 v6, v246
	v_readlane_b32 s2, v253, 0
	v_readlane_b32 s3, v253, 1
	s_nop 3
	s_load_dwordx2 s[12:13], s[2:3], 0xd0
	s_branch .Lp3_fft2
